# GEMM epilogues (in-proj, up-proj): the 8 row sum-of-squares loads of a unit are issued together instead of one load per vmcnt(0) wait
# speedup vs baseline: 1.0354x; 1.0089x over previous
.LBB0_120:
	v_lshl_add_u32 v140, s1, 8, v144
	v_ashrrev_i32_e32 v141, 31, v140
	v_lshl_add_u64 v[142:143], v[140:141], 3, s[14:15]
	global_load_dwordx2 v[150:151], v[142:143], off
	global_load_dwordx2 v[200:201], v[142:143], off offset:128
	global_load_dwordx2 v[202:203], v[142:143], off offset:256
	global_load_dwordx2 v[204:205], v[142:143], off offset:384
	global_load_dwordx2 v[206:207], v[142:143], off offset:1024
	global_load_dwordx2 v[208:209], v[142:143], off offset:1152
	global_load_dwordx2 v[210:211], v[142:143], off offset:1280
	global_load_dwordx2 v[212:213], v[142:143], off offset:1408
	s_lshl_b32 s1, s57, 8
	s_cmp_gt_i32 s57, 4
	s_waitcnt vmcnt(0)
	v_ffbh_u32_e32 v141, v151
	v_min_u32_e32 v141, 32, v141
	v_lshlrev_b64 v[150:151], v141, v[150:151]
	v_min_u32_e32 v149, 1, v150
	v_or_b32_e32 v149, v151, v149
	v_cvt_f32_u32_e32 v149, v149
	v_sub_u32_e32 v141, 32, v141
	v_ldexp_f32 v141, v149, v141
	v_mul_f32_e32 v141, 0x35800000, v141
	v_fmamk_f32 v141, v141, 0x3a800000, v182
	v_cmp_gt_f32_e32 vcc, s50, v141
	v_mul_f32_e32 v149, 0x4f800000, v141
	s_nop 0
	v_cndmask_b32_e32 v141, v141, v149, vcc
	v_sqrt_f32_e32 v149, v141
	s_nop 0
	v_add_u32_e32 v150, -1, v149
	v_fma_f32 v151, -v150, v149, v141
	v_cmp_ge_f32_e64 s[8:9], 0, v151
	v_add_u32_e32 v151, 1, v149
	s_nop 0
	v_cndmask_b32_e64 v150, v149, v150, s[8:9]
	v_fma_f32 v149, -v151, v149, v141
	v_cmp_lt_f32_e64 s[8:9], 0, v149
	s_nop 1
	v_cndmask_b32_e64 v149, v150, v151, s[8:9]
	v_mul_f32_e32 v150, 0x37800000, v149
	v_cndmask_b32_e32 v149, v149, v150, vcc
	v_cmp_class_f32_e32 vcc, v141, v183
	s_nop 1
	v_cndmask_b32_e32 v141, v149, v141, vcc
	v_div_scale_f32 v149, s[8:9], v141, v141, 1.0
	v_rcp_f32_e32 v150, v149
	s_nop 0
	v_fma_f32 v151, -v149, v150, 1.0
	v_fmac_f32_e32 v150, v151, v150
	v_div_scale_f32 v151, vcc, 1.0, v141, 1.0
	v_mul_f32_e32 v152, v151, v150
	v_fma_f32 v153, -v149, v152, v151
	v_fmac_f32_e32 v152, v153, v150
	v_fma_f32 v149, -v149, v152, v151
	v_div_fmas_f32 v149, v149, v150, v152
	v_div_fixup_f32 v150, v149, v141, 1.0
	v_pk_mul_f32 v[18:19], v[18:19], v[150:151] op_sel_hi:[1,0]
	v_pk_mul_f32 v[16:17], v[16:17], v[150:151] op_sel_hi:[1,0]
	v_pk_mul_f32 v[22:23], v[22:23], v[150:151] op_sel_hi:[1,0]
	v_pk_mul_f32 v[20:21], v[20:21], v[150:151] op_sel_hi:[1,0]
	v_pk_mul_f32 v[26:27], v[26:27], v[150:151] op_sel_hi:[1,0]
	v_pk_mul_f32 v[24:25], v[24:25], v[150:151] op_sel_hi:[1,0]
	v_pk_mul_f32 v[30:31], v[30:31], v[150:151] op_sel_hi:[1,0]
	v_pk_mul_f32 v[28:29], v[28:29], v[150:151] op_sel_hi:[1,0]
	v_mov_b32_e32 v150, v200
	v_mov_b32_e32 v151, v201
	v_ffbh_u32_e32 v141, v151
	v_min_u32_e32 v141, 32, v141
	v_lshlrev_b64 v[150:151], v141, v[150:151]
	v_min_u32_e32 v149, 1, v150
	v_or_b32_e32 v149, v151, v149
	v_cvt_f32_u32_e32 v149, v149
	v_sub_u32_e32 v141, 32, v141
	v_ldexp_f32 v141, v149, v141
	v_mul_f32_e32 v141, 0x35800000, v141
	v_fmamk_f32 v141, v141, 0x3a800000, v182
	v_cmp_gt_f32_e32 vcc, s50, v141
	v_mul_f32_e32 v149, 0x4f800000, v141
	s_nop 0
	v_cndmask_b32_e32 v141, v141, v149, vcc
	v_sqrt_f32_e32 v149, v141
	s_nop 0
	v_add_u32_e32 v150, -1, v149
	v_fma_f32 v151, -v150, v149, v141
	v_cmp_ge_f32_e64 s[8:9], 0, v151
	v_add_u32_e32 v151, 1, v149
	s_nop 0
	v_cndmask_b32_e64 v150, v149, v150, s[8:9]
	v_fma_f32 v149, -v151, v149, v141
	v_cmp_lt_f32_e64 s[8:9], 0, v149
	s_nop 1
	v_cndmask_b32_e64 v149, v150, v151, s[8:9]
	v_mul_f32_e32 v150, 0x37800000, v149
	v_cndmask_b32_e32 v149, v149, v150, vcc
	v_cmp_class_f32_e32 vcc, v141, v183
	s_nop 1
	v_cndmask_b32_e32 v141, v149, v141, vcc
	v_div_scale_f32 v149, s[8:9], v141, v141, 1.0
	v_rcp_f32_e32 v150, v149
	s_nop 0
	v_fma_f32 v151, -v149, v150, 1.0
	v_fmac_f32_e32 v150, v151, v150
	v_div_scale_f32 v151, vcc, 1.0, v141, 1.0
	v_mul_f32_e32 v152, v151, v150
	v_fma_f32 v153, -v149, v152, v151
	v_fmac_f32_e32 v152, v153, v150
	v_fma_f32 v149, -v149, v152, v151
	v_div_fmas_f32 v149, v149, v150, v152
	v_div_fixup_f32 v150, v149, v141, 1.0
	v_pk_mul_f32 v[50:51], v[50:51], v[150:151] op_sel_hi:[1,0]
	v_pk_mul_f32 v[48:49], v[48:49], v[150:151] op_sel_hi:[1,0]
	v_pk_mul_f32 v[54:55], v[54:55], v[150:151] op_sel_hi:[1,0]
	v_pk_mul_f32 v[52:53], v[52:53], v[150:151] op_sel_hi:[1,0]
	v_pk_mul_f32 v[58:59], v[58:59], v[150:151] op_sel_hi:[1,0]
	v_pk_mul_f32 v[56:57], v[56:57], v[150:151] op_sel_hi:[1,0]
	v_pk_mul_f32 v[62:63], v[62:63], v[150:151] op_sel_hi:[1,0]
	v_pk_mul_f32 v[60:61], v[60:61], v[150:151] op_sel_hi:[1,0]
	v_mov_b32_e32 v150, v202
	v_mov_b32_e32 v151, v203
	v_ffbh_u32_e32 v141, v151
	v_min_u32_e32 v141, 32, v141
	v_lshlrev_b64 v[150:151], v141, v[150:151]
	v_min_u32_e32 v149, 1, v150
	v_or_b32_e32 v149, v151, v149
	v_cvt_f32_u32_e32 v149, v149
	v_sub_u32_e32 v141, 32, v141
	v_ldexp_f32 v141, v149, v141
	v_mul_f32_e32 v141, 0x35800000, v141
	v_fmamk_f32 v141, v141, 0x3a800000, v182
	v_cmp_gt_f32_e32 vcc, s50, v141
	v_mul_f32_e32 v149, 0x4f800000, v141
	s_nop 0
	v_cndmask_b32_e32 v141, v141, v149, vcc
	v_sqrt_f32_e32 v149, v141
	s_nop 0
	v_add_u32_e32 v150, -1, v149
	v_fma_f32 v151, -v150, v149, v141
	v_cmp_ge_f32_e64 s[8:9], 0, v151
	v_add_u32_e32 v151, 1, v149
	s_nop 0
	v_cndmask_b32_e64 v150, v149, v150, s[8:9]
	v_fma_f32 v149, -v151, v149, v141
	v_cmp_lt_f32_e64 s[8:9], 0, v149
	s_nop 1
	v_cndmask_b32_e64 v149, v150, v151, s[8:9]
	v_mul_f32_e32 v150, 0x37800000, v149
	v_cndmask_b32_e32 v149, v149, v150, vcc
	v_cmp_class_f32_e32 vcc, v141, v183
	s_nop 1
	v_cndmask_b32_e32 v141, v149, v141, vcc
	v_div_scale_f32 v149, s[8:9], v141, v141, 1.0
	v_rcp_f32_e32 v150, v149
	s_nop 0
	v_fma_f32 v151, -v149, v150, 1.0
	v_fmac_f32_e32 v150, v151, v150
	v_div_scale_f32 v151, vcc, 1.0, v141, 1.0
	v_mul_f32_e32 v152, v151, v150
	v_fma_f32 v153, -v149, v152, v151
	v_fmac_f32_e32 v152, v153, v150
	v_fma_f32 v149, -v149, v152, v151
	v_div_fmas_f32 v149, v149, v150, v152
	v_div_fixup_f32 v150, v149, v141, 1.0
	v_pk_mul_f32 v[66:67], v[66:67], v[150:151] op_sel_hi:[1,0]
	v_pk_mul_f32 v[64:65], v[64:65], v[150:151] op_sel_hi:[1,0]
	v_pk_mul_f32 v[70:71], v[70:71], v[150:151] op_sel_hi:[1,0]
	v_pk_mul_f32 v[68:69], v[68:69], v[150:151] op_sel_hi:[1,0]
	v_pk_mul_f32 v[74:75], v[74:75], v[150:151] op_sel_hi:[1,0]
	v_pk_mul_f32 v[72:73], v[72:73], v[150:151] op_sel_hi:[1,0]
	v_pk_mul_f32 v[78:79], v[78:79], v[150:151] op_sel_hi:[1,0]
	v_pk_mul_f32 v[76:77], v[76:77], v[150:151] op_sel_hi:[1,0]
	v_mov_b32_e32 v150, v204
	v_mov_b32_e32 v151, v205
	v_ffbh_u32_e32 v141, v151
	v_min_u32_e32 v141, 32, v141
	v_lshlrev_b64 v[150:151], v141, v[150:151]
	v_min_u32_e32 v149, 1, v150
	v_or_b32_e32 v149, v151, v149
	v_cvt_f32_u32_e32 v149, v149
	v_sub_u32_e32 v141, 32, v141
	v_ldexp_f32 v141, v149, v141
	v_mul_f32_e32 v141, 0x35800000, v141
	v_fmamk_f32 v141, v141, 0x3a800000, v182
	v_cmp_gt_f32_e32 vcc, s50, v141
	v_mul_f32_e32 v149, 0x4f800000, v141
	s_nop 0
	v_cndmask_b32_e32 v141, v141, v149, vcc
	v_sqrt_f32_e32 v149, v141
	s_nop 0
	v_add_u32_e32 v150, -1, v149
	v_fma_f32 v151, -v150, v149, v141
	v_cmp_ge_f32_e64 s[8:9], 0, v151
	v_add_u32_e32 v151, 1, v149
	s_nop 0
	v_cndmask_b32_e64 v150, v149, v150, s[8:9]
	v_fma_f32 v149, -v151, v149, v141
	v_cmp_lt_f32_e64 s[8:9], 0, v149
	s_nop 1
	v_cndmask_b32_e64 v149, v150, v151, s[8:9]
	v_mul_f32_e32 v150, 0x37800000, v149
	v_cndmask_b32_e32 v149, v149, v150, vcc
	v_cmp_class_f32_e32 vcc, v141, v183
	s_nop 1
	v_cndmask_b32_e32 v141, v149, v141, vcc
	v_div_scale_f32 v149, s[8:9], v141, v141, 1.0
	v_rcp_f32_e32 v150, v149
	s_nop 0
	v_fma_f32 v151, -v149, v150, 1.0
	v_fmac_f32_e32 v150, v151, v150
	v_div_scale_f32 v151, vcc, 1.0, v141, 1.0
	v_mul_f32_e32 v152, v151, v150
	v_fma_f32 v153, -v149, v152, v151
	v_fmac_f32_e32 v152, v153, v150
	v_fma_f32 v149, -v149, v152, v151
	v_div_fmas_f32 v149, v149, v150, v152
	v_div_fixup_f32 v150, v149, v141, 1.0
	v_pk_mul_f32 v[98:99], v[98:99], v[150:151] op_sel_hi:[1,0]
	v_pk_mul_f32 v[96:97], v[96:97], v[150:151] op_sel_hi:[1,0]
	v_pk_mul_f32 v[102:103], v[102:103], v[150:151] op_sel_hi:[1,0]
	v_pk_mul_f32 v[100:101], v[100:101], v[150:151] op_sel_hi:[1,0]
	v_pk_mul_f32 v[106:107], v[106:107], v[150:151] op_sel_hi:[1,0]
	v_pk_mul_f32 v[104:105], v[104:105], v[150:151] op_sel_hi:[1,0]
	v_pk_mul_f32 v[110:111], v[110:111], v[150:151] op_sel_hi:[1,0]
	v_pk_mul_f32 v[108:109], v[108:109], v[150:151] op_sel_hi:[1,0]
	v_mov_b32_e32 v150, v206
	v_mov_b32_e32 v151, v207
	v_ffbh_u32_e32 v141, v151
	v_min_u32_e32 v141, 32, v141
	v_lshlrev_b64 v[150:151], v141, v[150:151]
	v_min_u32_e32 v149, 1, v150
	v_or_b32_e32 v149, v151, v149
	v_cvt_f32_u32_e32 v149, v149
	v_sub_u32_e32 v141, 32, v141
	v_ldexp_f32 v141, v149, v141
	v_mul_f32_e32 v141, 0x35800000, v141
	v_fmamk_f32 v141, v141, 0x3a800000, v182
	v_cmp_gt_f32_e32 vcc, s50, v141
	v_mul_f32_e32 v149, 0x4f800000, v141
	s_nop 0
	v_cndmask_b32_e32 v141, v141, v149, vcc
	v_sqrt_f32_e32 v149, v141
	s_nop 0
	v_add_u32_e32 v150, -1, v149
	v_fma_f32 v151, -v150, v149, v141
	v_cmp_ge_f32_e64 s[8:9], 0, v151
	v_add_u32_e32 v151, 1, v149
	s_nop 0
	v_cndmask_b32_e64 v150, v149, v150, s[8:9]
	v_fma_f32 v149, -v151, v149, v141
	v_cmp_lt_f32_e64 s[8:9], 0, v149
	s_nop 1
	v_cndmask_b32_e64 v149, v150, v151, s[8:9]
	v_mul_f32_e32 v150, 0x37800000, v149
	v_cndmask_b32_e32 v149, v149, v150, vcc
	v_cmp_class_f32_e32 vcc, v141, v183
	s_nop 1
	v_cndmask_b32_e32 v141, v149, v141, vcc
	v_div_scale_f32 v149, s[8:9], v141, v141, 1.0
	v_rcp_f32_e32 v150, v149
	s_nop 0
	v_fma_f32 v151, -v149, v150, 1.0
	v_fmac_f32_e32 v150, v151, v150
	v_div_scale_f32 v151, vcc, 1.0, v141, 1.0
	v_mul_f32_e32 v152, v151, v150
	v_fma_f32 v153, -v149, v152, v151
	v_fmac_f32_e32 v152, v153, v150
	v_fma_f32 v149, -v149, v152, v151
	v_div_fmas_f32 v149, v149, v150, v152
	v_div_fixup_f32 v150, v149, v141, 1.0
	v_pk_mul_f32 v[114:115], v[114:115], v[150:151] op_sel_hi:[1,0]
	v_pk_mul_f32 v[112:113], v[112:113], v[150:151] op_sel_hi:[1,0]
	v_pk_mul_f32 v[118:119], v[118:119], v[150:151] op_sel_hi:[1,0]
	v_pk_mul_f32 v[116:117], v[116:117], v[150:151] op_sel_hi:[1,0]
	v_pk_mul_f32 v[122:123], v[122:123], v[150:151] op_sel_hi:[1,0]
	v_pk_mul_f32 v[120:121], v[120:121], v[150:151] op_sel_hi:[1,0]
	v_pk_mul_f32 v[126:127], v[126:127], v[150:151] op_sel_hi:[1,0]
	v_pk_mul_f32 v[124:125], v[124:125], v[150:151] op_sel_hi:[1,0]
	v_mov_b32_e32 v150, v208
	v_mov_b32_e32 v151, v209
	v_ffbh_u32_e32 v141, v151
	v_min_u32_e32 v141, 32, v141
	v_lshlrev_b64 v[150:151], v141, v[150:151]
	v_min_u32_e32 v149, 1, v150
	v_or_b32_e32 v149, v151, v149
	v_cvt_f32_u32_e32 v149, v149
	v_sub_u32_e32 v141, 32, v141
	v_ldexp_f32 v141, v149, v141
	v_mul_f32_e32 v141, 0x35800000, v141
	v_fmamk_f32 v141, v141, 0x3a800000, v182
	v_cmp_gt_f32_e32 vcc, s50, v141
	v_mul_f32_e32 v149, 0x4f800000, v141
	s_nop 0
	v_cndmask_b32_e32 v141, v141, v149, vcc
	v_sqrt_f32_e32 v149, v141
	s_nop 0
	v_add_u32_e32 v150, -1, v149
	v_fma_f32 v151, -v150, v149, v141
	v_cmp_ge_f32_e64 s[8:9], 0, v151
	v_add_u32_e32 v151, 1, v149
	s_nop 0
	v_cndmask_b32_e64 v150, v149, v150, s[8:9]
	v_fma_f32 v149, -v151, v149, v141
	v_cmp_lt_f32_e64 s[8:9], 0, v149
	s_nop 1
	v_cndmask_b32_e64 v149, v150, v151, s[8:9]
	v_mul_f32_e32 v150, 0x37800000, v149
	v_cndmask_b32_e32 v149, v149, v150, vcc
	v_cmp_class_f32_e32 vcc, v141, v183
	s_nop 1
	v_cndmask_b32_e32 v141, v149, v141, vcc
	v_div_scale_f32 v149, s[8:9], v141, v141, 1.0
	v_rcp_f32_e32 v150, v149
	s_nop 0
	v_fma_f32 v151, -v149, v150, 1.0
	v_fmac_f32_e32 v150, v151, v150
	v_div_scale_f32 v151, vcc, 1.0, v141, 1.0
	v_mul_f32_e32 v152, v151, v150
	v_fma_f32 v153, -v149, v152, v151
	v_fmac_f32_e32 v152, v153, v150
	v_fma_f32 v149, -v149, v152, v151
	v_div_fmas_f32 v149, v149, v150, v152
	v_div_fixup_f32 v150, v149, v141, 1.0
	v_pk_mul_f32 v[94:95], v[94:95], v[150:151] op_sel_hi:[1,0]
	v_pk_mul_f32 v[92:93], v[92:93], v[150:151] op_sel_hi:[1,0]
	v_pk_mul_f32 v[90:91], v[90:91], v[150:151] op_sel_hi:[1,0]
	v_pk_mul_f32 v[88:89], v[88:89], v[150:151] op_sel_hi:[1,0]
	v_pk_mul_f32 v[86:87], v[86:87], v[150:151] op_sel_hi:[1,0]
	v_pk_mul_f32 v[84:85], v[84:85], v[150:151] op_sel_hi:[1,0]
	v_pk_mul_f32 v[82:83], v[82:83], v[150:151] op_sel_hi:[1,0]
	v_pk_mul_f32 v[80:81], v[80:81], v[150:151] op_sel_hi:[1,0]
	v_mov_b32_e32 v150, v210
	v_mov_b32_e32 v151, v211
	v_ffbh_u32_e32 v141, v151
	v_mov_b32_e32 v142, v212
	v_mov_b32_e32 v143, v213
	v_min_u32_e32 v141, 32, v141
	v_lshlrev_b64 v[150:151], v141, v[150:151]
	v_min_u32_e32 v149, 1, v150
	v_or_b32_e32 v149, v151, v149
	v_cvt_f32_u32_e32 v149, v149
	v_sub_u32_e32 v141, 32, v141
	v_ldexp_f32 v141, v149, v141
	v_mul_f32_e32 v141, 0x35800000, v141
	v_fmamk_f32 v141, v141, 0x3a800000, v182
	v_cmp_gt_f32_e32 vcc, s50, v141
	v_mul_f32_e32 v149, 0x4f800000, v141
	s_nop 0
	v_cndmask_b32_e32 v141, v141, v149, vcc
	v_sqrt_f32_e32 v149, v141
	s_nop 0
	v_add_u32_e32 v150, -1, v149
	v_fma_f32 v151, -v150, v149, v141
	v_cmp_ge_f32_e64 s[8:9], 0, v151
	v_add_u32_e32 v151, 1, v149
	s_nop 0
	v_cndmask_b32_e64 v150, v149, v150, s[8:9]
	v_fma_f32 v149, -v151, v149, v141
	v_cmp_lt_f32_e64 s[8:9], 0, v149
	s_nop 1
	v_cndmask_b32_e64 v149, v150, v151, s[8:9]
	v_mul_f32_e32 v150, 0x37800000, v149
	v_cndmask_b32_e32 v149, v149, v150, vcc
	v_cmp_class_f32_e32 vcc, v141, v183
	s_nop 1
	v_cndmask_b32_e32 v141, v149, v141, vcc
	v_div_scale_f32 v149, s[8:9], v141, v141, 1.0
	v_rcp_f32_e32 v150, v149
	s_nop 0
	v_fma_f32 v151, -v149, v150, 1.0
	v_fmac_f32_e32 v150, v151, v150
	v_div_scale_f32 v151, vcc, 1.0, v141, 1.0
	v_mul_f32_e32 v152, v151, v150
	v_fma_f32 v153, -v149, v152, v151
	v_fmac_f32_e32 v152, v153, v150
	v_fma_f32 v149, -v149, v152, v151
	v_div_fmas_f32 v149, v149, v150, v152
	v_div_fixup_f32 v150, v149, v141, 1.0
	v_pk_mul_f32 v[46:47], v[46:47], v[150:151] op_sel_hi:[1,0]
	v_pk_mul_f32 v[44:45], v[44:45], v[150:151] op_sel_hi:[1,0]
	v_pk_mul_f32 v[42:43], v[42:43], v[150:151] op_sel_hi:[1,0]
	v_pk_mul_f32 v[40:41], v[40:41], v[150:151] op_sel_hi:[1,0]
	v_pk_mul_f32 v[38:39], v[38:39], v[150:151] op_sel_hi:[1,0]
	v_pk_mul_f32 v[36:37], v[36:37], v[150:151] op_sel_hi:[1,0]
	v_pk_mul_f32 v[34:35], v[34:35], v[150:151] op_sel_hi:[1,0]
	v_pk_mul_f32 v[32:33], v[32:33], v[150:151] op_sel_hi:[1,0]
	v_or_b32_e32 v152, 16, v140
	v_ffbh_u32_e32 v141, v143
	v_min_u32_e32 v141, 32, v141
	v_lshlrev_b64 v[142:143], v141, v[142:143]
	v_min_u32_e32 v142, 1, v142
	v_or_b32_e32 v142, v143, v142
	v_cvt_f32_u32_e32 v142, v142
	v_sub_u32_e32 v141, 32, v141
	v_ldexp_f32 v141, v142, v141
	v_mul_f32_e32 v141, 0x35800000, v141
	v_fmamk_f32 v141, v141, 0x3a800000, v182
	v_cmp_gt_f32_e32 vcc, s50, v141
	v_mul_f32_e32 v142, 0x4f800000, v141
	s_nop 0
	v_cndmask_b32_e32 v141, v141, v142, vcc
	v_sqrt_f32_e32 v142, v141
	s_nop 0
	v_add_u32_e32 v143, -1, v142
	v_fma_f32 v149, -v143, v142, v141
	v_cmp_ge_f32_e64 s[8:9], 0, v149
	v_add_u32_e32 v149, 1, v142
	s_nop 0
	v_cndmask_b32_e64 v143, v142, v143, s[8:9]
	v_fma_f32 v142, -v149, v142, v141
	v_cmp_lt_f32_e64 s[8:9], 0, v142
	s_nop 1
	v_cndmask_b32_e64 v142, v143, v149, s[8:9]
	v_mul_f32_e32 v143, 0x37800000, v142
	v_cndmask_b32_e32 v142, v142, v143, vcc
	v_cmp_class_f32_e32 vcc, v141, v183
	s_nop 1
	v_cndmask_b32_e32 v141, v142, v141, vcc
	v_div_scale_f32 v142, s[8:9], v141, v141, 1.0
	v_rcp_f32_e32 v143, v142
	s_mov_b64 s[8:9], -1
	v_fma_f32 v149, -v142, v143, 1.0
	v_fmac_f32_e32 v143, v149, v143
	v_div_scale_f32 v149, vcc, 1.0, v141, 1.0
	v_mul_f32_e32 v150, v149, v143
	v_fma_f32 v151, -v142, v150, v149
	v_fmac_f32_e32 v150, v151, v143
	v_fma_f32 v142, -v142, v150, v149
	v_div_fmas_f32 v142, v142, v143, v150
	v_div_fixup_f32 v142, v142, v141, 1.0
	v_pk_mul_f32 v[14:15], v[14:15], v[142:143] op_sel_hi:[1,0]
	v_pk_mul_f32 v[12:13], v[12:13], v[142:143] op_sel_hi:[1,0]
	v_pk_mul_f32 v[10:11], v[10:11], v[142:143] op_sel_hi:[1,0]
	v_pk_mul_f32 v[8:9], v[8:9], v[142:143] op_sel_hi:[1,0]
	v_pk_mul_f32 v[6:7], v[6:7], v[142:143] op_sel_hi:[1,0]
	v_pk_mul_f32 v[4:5], v[4:5], v[142:143] op_sel_hi:[1,0]
	v_pk_mul_f32 v[2:3], v[2:3], v[142:143] op_sel_hi:[1,0]
	v_pk_mul_f32 v[0:1], v[0:1], v[142:143] op_sel_hi:[1,0]
	v_or_b32_e32 v151, 32, v140
	v_or_b32_e32 v150, 48, v140
	v_add_u32_e32 v149, 0x80, v140
	v_add_u32_e32 v143, 0x90, v140
	v_add_u32_e32 v142, 0xa0, v140
	v_add_u32_e32 v141, 0xb0, v140
	s_cbranch_scc0 .LBB0_122
	v_add_u32_e32 v160, s1, v147
	v_mov_b64_e32 v[158:159], s[12:13]
	v_mad_i64_i32 v[154:155], s[8:9], v140, s78, v[158:159]
	v_lshlrev_b64 v[170:171], 1, v[160:161]
	v_lshl_add_u64 v[174:175], v[154:155], 0, v[170:171]
	v_cvt_pk_bf16_f32 v154, v16, v17
	v_cvt_pk_bf16_f32 v155, v18, v19
	v_cvt_pk_bf16_f32 v156, v20, v21
	v_cvt_pk_bf16_f32 v157, v22, v23
	global_store_dwordx4 v[174:175], v[154:157], off
	s_nop 1
	v_cvt_pk_bf16_f32 v154, v24, v25
	v_cvt_pk_bf16_f32 v155, v26, v27
	v_cvt_pk_bf16_f32 v156, v28, v29
	v_cvt_pk_bf16_f32 v157, v30, v31
	global_store_dwordx4 v[174:175], v[154:157], off offset:256
	s_nop 1
	v_mad_i64_i32 v[154:155], s[8:9], v152, s78, v[158:159]
	v_lshl_add_u64 v[174:175], v[154:155], 0, v[170:171]
	v_cvt_pk_bf16_f32 v154, v48, v49
	v_cvt_pk_bf16_f32 v155, v50, v51
	v_cvt_pk_bf16_f32 v156, v52, v53
	v_cvt_pk_bf16_f32 v157, v54, v55
	global_store_dwordx4 v[174:175], v[154:157], off
	s_nop 1
	v_cvt_pk_bf16_f32 v154, v56, v57
	v_cvt_pk_bf16_f32 v155, v58, v59
	v_cvt_pk_bf16_f32 v156, v60, v61
	v_cvt_pk_bf16_f32 v157, v62, v63
	global_store_dwordx4 v[174:175], v[154:157], off offset:256
	s_nop 1
	v_mad_i64_i32 v[154:155], s[8:9], v151, s78, v[158:159]
	v_lshl_add_u64 v[174:175], v[154:155], 0, v[170:171]
	v_cvt_pk_bf16_f32 v154, v64, v65
	v_cvt_pk_bf16_f32 v155, v66, v67
	v_cvt_pk_bf16_f32 v156, v68, v69
	v_cvt_pk_bf16_f32 v157, v70, v71
	global_store_dwordx4 v[174:175], v[154:157], off
	s_nop 1
	v_cvt_pk_bf16_f32 v154, v72, v73
	v_cvt_pk_bf16_f32 v155, v74, v75
	v_cvt_pk_bf16_f32 v156, v76, v77
	v_cvt_pk_bf16_f32 v157, v78, v79
	global_store_dwordx4 v[174:175], v[154:157], off offset:256
	s_nop 1
	v_mad_i64_i32 v[154:155], s[8:9], v150, s78, v[158:159]
	v_lshl_add_u64 v[174:175], v[154:155], 0, v[170:171]
	v_cvt_pk_bf16_f32 v154, v96, v97
	v_cvt_pk_bf16_f32 v155, v98, v99
	v_cvt_pk_bf16_f32 v156, v100, v101
	v_cvt_pk_bf16_f32 v157, v102, v103
	global_store_dwordx4 v[174:175], v[154:157], off
	s_nop 1
	v_cvt_pk_bf16_f32 v154, v104, v105
	v_cvt_pk_bf16_f32 v155, v106, v107
	v_cvt_pk_bf16_f32 v156, v108, v109
	v_cvt_pk_bf16_f32 v157, v110, v111
	global_store_dwordx4 v[174:175], v[154:157], off offset:256
	s_nop 1
	v_mad_i64_i32 v[154:155], s[8:9], v149, s78, v[158:159]
	v_lshl_add_u64 v[174:175], v[154:155], 0, v[170:171]
	v_cvt_pk_bf16_f32 v154, v112, v113
	v_cvt_pk_bf16_f32 v155, v114, v115
	v_cvt_pk_bf16_f32 v156, v116, v117
	v_cvt_pk_bf16_f32 v157, v118, v119
	global_store_dwordx4 v[174:175], v[154:157], off
	s_nop 1
	v_cvt_pk_bf16_f32 v154, v120, v121
	v_cvt_pk_bf16_f32 v155, v122, v123
	v_cvt_pk_bf16_f32 v156, v124, v125
	v_cvt_pk_bf16_f32 v157, v126, v127
	global_store_dwordx4 v[174:175], v[154:157], off offset:256
	s_nop 1
	v_mad_i64_i32 v[154:155], s[8:9], v143, s78, v[158:159]
	v_lshl_add_u64 v[174:175], v[154:155], 0, v[170:171]
	v_cvt_pk_bf16_f32 v154, v92, v93
	v_cvt_pk_bf16_f32 v155, v94, v95
	v_cvt_pk_bf16_f32 v156, v88, v89
	v_cvt_pk_bf16_f32 v157, v90, v91
	global_store_dwordx4 v[174:175], v[154:157], off
	s_nop 1
	v_cvt_pk_bf16_f32 v154, v84, v85
	v_cvt_pk_bf16_f32 v155, v86, v87
	v_cvt_pk_bf16_f32 v156, v80, v81
	v_cvt_pk_bf16_f32 v157, v82, v83
	global_store_dwordx4 v[174:175], v[154:157], off offset:256
	s_nop 1
	v_mad_i64_i32 v[154:155], s[8:9], v142, s78, v[158:159]
	v_lshl_add_u64 v[174:175], v[154:155], 0, v[170:171]
	v_cvt_pk_bf16_f32 v154, v44, v45
	v_cvt_pk_bf16_f32 v155, v46, v47
	v_cvt_pk_bf16_f32 v156, v40, v41
	v_cvt_pk_bf16_f32 v157, v42, v43
	global_store_dwordx4 v[174:175], v[154:157], off
	s_nop 1
	v_cvt_pk_bf16_f32 v154, v36, v37
	v_cvt_pk_bf16_f32 v155, v38, v39
	v_cvt_pk_bf16_f32 v156, v32, v33
	v_cvt_pk_bf16_f32 v157, v34, v35
	global_store_dwordx4 v[174:175], v[154:157], off offset:256
	s_nop 1
	v_mad_i64_i32 v[154:155], s[8:9], v141, s78, v[158:159]
	v_lshl_add_u64 v[158:159], v[154:155], 0, v[170:171]
	v_cvt_pk_bf16_f32 v154, v12, v13
	v_cvt_pk_bf16_f32 v155, v14, v15
	v_cvt_pk_bf16_f32 v156, v8, v9
	v_cvt_pk_bf16_f32 v157, v10, v11
	global_store_dwordx4 v[158:159], v[154:157], off
	s_mov_b64 s[8:9], 0
	s_nop 0
	v_cvt_pk_bf16_f32 v154, v4, v5
	v_cvt_pk_bf16_f32 v155, v6, v7
	v_cvt_pk_bf16_f32 v156, v0, v1
	v_cvt_pk_bf16_f32 v157, v2, v3
	global_store_dwordx4 v[158:159], v[154:157], off offset:256

.LBB0_656:
	v_lshl_add_u32 v140, s51, 8, v142
	v_ashrrev_i32_e32 v141, 31, v140
	v_lshl_add_u64 v[138:139], v[140:141], 3, s[16:17]
	global_load_dwordx2 v[146:147], v[138:139], off
	global_load_dwordx2 v[200:201], v[138:139], off offset:128
	global_load_dwordx2 v[202:203], v[138:139], off offset:256
	global_load_dwordx2 v[204:205], v[138:139], off offset:384
	global_load_dwordx2 v[206:207], v[138:139], off offset:1024
	global_load_dwordx2 v[208:209], v[138:139], off offset:1152
	global_load_dwordx2 v[210:211], v[138:139], off offset:1280
	global_load_dwordx2 v[212:213], v[138:139], off offset:1408
	v_max_f32_e32 v120, v120, v120
	v_max_f32_e32 v126, v126, v126
	v_max_f32_e32 v112, v112, v112
	v_max_f32_e32 v124, v124, v124
	v_max_f32_e32 v150, v116, v116
	v_max_f32_e32 v152, v118, v118
	v_max_f32_e32 v114, v114, v114
	v_max_f32_e32 v118, 0, v120
	v_max_f32_e32 v120, 0, v126
	v_max_f32_e32 v126, 0, v112
	v_max_f32_e32 v121, v121, v121
	v_max_f32_e32 v127, v127, v127
	v_max_f32_e32 v113, v113, v113
	v_max_f32_e32 v116, 0, v124
	v_max_f32_e32 v124, 0, v150
	v_max_f32_e32 v150, 0, v152
	v_max_f32_e32 v152, 0, v114
	v_max_f32_e32 v153, v119, v119
	v_max_f32_e32 v119, 0, v121
	v_max_f32_e32 v121, 0, v127
	v_max_f32_e32 v127, 0, v113
	v_lshl_or_b32 v148, s1, 8, v144
	v_max_f32_e32 v125, v125, v125
	v_max_f32_e32 v151, v117, v117
	v_max_f32_e32 v115, v115, v115
	v_ashrrev_i32_e32 v149, 31, v148
	v_max_f32_e32 v117, 0, v125
	v_max_f32_e32 v125, 0, v151
	v_max_f32_e32 v151, 0, v153
	v_max_f32_e32 v153, 0, v115
	v_max_f32_e32 v122, v122, v122
	v_max_f32_e32 v123, v123, v123
	v_max_f32_e32 v122, 0, v122
	v_max_f32_e32 v123, 0, v123
	v_max_f32_e32 v109, v109, v109
	v_max_f32_e32 v97, v97, v97
	v_max_f32_e32 v111, v111, v111
	v_max_f32_e32 v105, v105, v105
	v_max_f32_e32 v107, v107, v107
	v_max_f32_e32 v104, v104, v104
	v_max_f32_e32 v110, v110, v110
	v_max_f32_e32 v106, v106, v106
	v_max_f32_e32 v108, v108, v108
	v_max_f32_e32 v93, v93, v93
	v_max_f32_e32 v81, v81, v81
	v_max_f32_e32 v95, v95, v95
	v_max_f32_e32 v89, v89, v89
	v_max_f32_e32 v91, v91, v91
	v_max_f32_e32 v88, v88, v88
	v_max_f32_e32 v94, v94, v94
	v_max_f32_e32 v90, v90, v90
	v_max_f32_e32 v92, v92, v92
	v_max_f32_e32 v77, v77, v77
	v_max_f32_e32 v65, v65, v65
	v_max_f32_e32 v79, v79, v79
	v_max_f32_e32 v73, v73, v73
	v_max_f32_e32 v75, v75, v75
	v_max_f32_e32 v72, v72, v72
	v_max_f32_e32 v78, v78, v78
	v_max_f32_e32 v74, v74, v74
	v_max_f32_e32 v76, v76, v76
	v_max_f32_e32 v60, v60, v60
	v_max_f32_e32 v63, v63, v63
	v_max_f32_e32 v61, v61, v61
	v_max_f32_e32 v56, v56, v56
	v_max_f32_e32 v58, v58, v58
	v_max_f32_e32 v57, v57, v57
	v_max_f32_e32 v59, v59, v59
	v_max_f32_e32 v62, v62, v62
	s_mov_b32 s1, 0x100000
	v_max_f32_e32 v44, v44, v44
	v_max_f32_e32 v47, v47, v47
	v_max_f32_e32 v45, v45, v45
	v_max_f32_e32 v40, v40, v40
	v_max_f32_e32 v42, v42, v42
	v_max_f32_e32 v41, v41, v41
	v_max_f32_e32 v43, v43, v43
	v_max_f32_e32 v46, v46, v46
	v_max_f32_e32 v28, v28, v28
	s_waitcnt vmcnt(0)
	v_ffbh_u32_e32 v112, v147
	v_min_u32_e32 v114, 32, v112
	v_lshlrev_b64 v[112:113], v114, v[146:147]
	v_min_u32_e32 v112, 1, v112
	v_or_b32_e32 v112, v113, v112
	v_cvt_f32_u32_e32 v112, v112
	v_sub_u32_e32 v113, 32, v114
	v_lshlrev_b64 v[114:115], 1, v[148:149]
	v_max_f32_e32 v31, v31, v31
	v_ldexp_f32 v112, v112, v113
	v_mul_f32_e32 v112, 0x35800000, v112
	v_fmamk_f32 v112, v112, 0x3a800000, v182
	v_mul_f32_e32 v113, 0x4f800000, v112
	v_cmp_gt_f32_e32 vcc, s50, v112
	v_max_f32_e32 v29, v29, v29
	v_max_f32_e32 v24, v24, v24
	v_cndmask_b32_e32 v146, v112, v113, vcc
	v_sqrt_f32_e32 v147, v146
	v_lshlrev_b64 v[112:113], 13, v[140:141]
	v_lshl_add_u64 v[112:113], s[14:15], 0, v[112:113]
	v_lshl_add_u64 v[112:113], v[112:113], 0, v[114:115]
	v_add_u32_e32 v141, -1, v147
	v_add_u32_e32 v148, 1, v147
	v_fma_f32 v149, -v141, v147, v146
	v_fma_f32 v154, -v148, v147, v146
	v_cmp_ge_f32_e64 s[10:11], 0, v149
	v_max_f32_e32 v26, v26, v26
	v_max_f32_e32 v25, v25, v25
	v_cndmask_b32_e64 v141, v147, v141, s[10:11]
	v_cmp_lt_f32_e64 s[10:11], 0, v154
	v_max_f32_e32 v27, v27, v27
	v_max_f32_e32 v30, v30, v30
	v_cndmask_b32_e64 v141, v141, v148, s[10:11]
	v_mul_f32_e32 v147, 0x37800000, v141
	v_cndmask_b32_e32 v141, v141, v147, vcc
	v_cmp_class_f32_e32 vcc, v146, v183
	v_max_f32_e32 v13, v13, v13
	v_max_f32_e32 v8, v8, v8
	v_cndmask_b32_e32 v141, v141, v146, vcc
	v_div_scale_f32 v146, s[10:11], v141, v141, 1.0
	v_rcp_f32_e32 v147, v146
	v_div_scale_f32 v148, vcc, 1.0, v141, 1.0
	v_max_f32_e32 v14, v14, v14
	v_fma_f32 v149, -v146, v147, 1.0
	v_fmac_f32_e32 v147, v149, v147
	v_mul_f32_e32 v149, v148, v147
	v_fma_f32 v154, -v146, v149, v148
	v_fmac_f32_e32 v149, v154, v147
	v_fma_f32 v146, -v146, v149, v148
	v_div_fmas_f32 v146, v146, v147, v149
	v_div_fixup_f32 v146, v146, v141, 1.0
	v_pk_mul_f32 v[116:117], v[116:117], v[146:147] op_sel_hi:[1,0]
	v_pk_mul_f32 v[118:119], v[118:119], v[146:147] op_sel_hi:[1,0]
	v_pk_mul_f32 v[120:121], v[120:121], v[146:147] op_sel_hi:[1,0]
	v_pk_mul_f32 v[122:123], v[122:123], v[146:147] op_sel_hi:[1,0]
	v_pk_mul_f32 v[124:125], v[124:125], v[146:147] op_sel_hi:[1,0]
	v_pk_mul_f32 v[126:127], v[126:127], v[146:147] op_sel_hi:[1,0]
	v_pk_mul_f32 v[148:149], v[150:151], v[146:147] op_sel_hi:[1,0]
	v_pk_mul_f32 v[146:147], v[152:153], v[146:147] op_sel_hi:[1,0]
	v_pk_mul_f32 v[116:117], v[116:117], v[116:117]
	v_pk_mul_f32 v[118:119], v[118:119], v[118:119]
	v_pk_mul_f32 v[120:121], v[120:121], v[120:121]
	v_pk_mul_f32 v[122:123], v[122:123], v[122:123]
	v_pk_mul_f32 v[124:125], v[124:125], v[124:125]
	v_pk_mul_f32 v[126:127], v[126:127], v[126:127]
	v_pk_mul_f32 v[148:149], v[148:149], v[148:149]
	v_pk_mul_f32 v[146:147], v[146:147], v[146:147]
	v_cvt_pk_bf16_f32 v116, v116, v117
	v_cvt_pk_bf16_f32 v117, v120, v121
	v_cvt_pk_bf16_f32 v118, v118, v119
	v_cvt_pk_bf16_f32 v119, v122, v123
	v_cvt_pk_bf16_f32 v120, v124, v125
	v_cvt_pk_bf16_f32 v121, v148, v149
	v_cvt_pk_bf16_f32 v122, v126, v127
	v_cvt_pk_bf16_f32 v123, v146, v147
	global_store_dwordx4 v[112:113], v[116:119], off
	global_store_dwordx4 v[112:113], v[120:123], off offset:256
	s_nop 1
	v_mov_b32_e32 v116, v200
	v_mov_b32_e32 v117, v201
	v_max_f32_e32 v124, v99, v99
	v_max_f32_e32 v99, 0, v109
	v_max_f32_e32 v109, 0, v97
	v_max_f32_e32 v123, v103, v103
	v_max_f32_e32 v103, 0, v111
	v_max_f32_e32 v120, v101, v101
	v_max_f32_e32 v118, v100, v100
	v_max_f32_e32 v121, v102, v102
	v_max_f32_e32 v122, v98, v98
	v_max_f32_e32 v101, 0, v105
	v_max_f32_e32 v105, 0, v107
	v_max_f32_e32 v107, 0, v120
	v_max_f32_e32 v100, 0, v104
	v_max_f32_e32 v102, 0, v110
	v_max_f32_e32 v104, 0, v106
	v_max_f32_e32 v106, 0, v118
	v_max_f32_e32 v110, 0, v121
	v_max_f32_e32 v118, 0, v122
	v_max_f32_e32 v119, v96, v96
	v_or_b32_e32 v96, 16, v140
	v_max_f32_e32 v98, 0, v108
	v_max_f32_e32 v108, 0, v119
	v_max_f32_e32 v119, 0, v124
	v_max_f32_e32 v15, v15, v15
	v_max_f32_e32 v10, v10, v10
	v_max_f32_e32 v9, v9, v9
	v_max_f32_e32 v12, v12, v12
	v_max_f32_e32 v11, v11, v11
	v_readlane_b32 s62, v254, 61
	v_readlane_b32 s66, v254, 63
	v_readlane_b32 s63, v254, 62
	v_readlane_b32 s67, v255, 0
	v_ffbh_u32_e32 v97, v117
	v_min_u32_e32 v97, 32, v97
	v_lshlrev_b64 v[116:117], v97, v[116:117]
	v_min_u32_e32 v111, 1, v116
	v_or_b32_e32 v111, v117, v111
	v_cvt_f32_u32_e32 v116, v111
	v_sub_u32_e32 v97, 32, v97
	v_max_f32_e32 v111, 0, v123
	v_ldexp_f32 v97, v116, v97
	v_mul_f32_e32 v97, 0x35800000, v97
	v_fmamk_f32 v97, v97, 0x3a800000, v182
	v_mul_f32_e32 v116, 0x4f800000, v97
	v_cmp_gt_f32_e32 vcc, s50, v97
	s_nop 1
	v_cndmask_b32_e32 v116, v97, v116, vcc
	v_sqrt_f32_e32 v117, v116
	v_ashrrev_i32_e32 v97, 31, v96
	v_lshlrev_b64 v[96:97], 13, v[96:97]
	v_lshl_add_u64 v[96:97], s[14:15], 0, v[96:97]
	v_add_u32_e32 v120, -1, v117
	v_add_u32_e32 v121, 1, v117
	v_fma_f32 v122, -v120, v117, v116
	v_fma_f32 v123, -v121, v117, v116
	v_cmp_ge_f32_e64 s[10:11], 0, v122
	s_nop 1
	v_cndmask_b32_e64 v117, v117, v120, s[10:11]
	v_cmp_lt_f32_e64 s[10:11], 0, v123
	s_nop 1
	v_cndmask_b32_e64 v117, v117, v121, s[10:11]
	v_mul_f32_e32 v120, 0x37800000, v117
	v_cndmask_b32_e32 v117, v117, v120, vcc
	v_cmp_class_f32_e32 vcc, v116, v183
	s_nop 1
	v_cndmask_b32_e32 v120, v117, v116, vcc
	v_div_scale_f32 v121, s[10:11], v120, v120, 1.0
	v_rcp_f32_e32 v122, v121
	v_lshl_add_u64 v[116:117], v[96:97], 0, v[114:115]
	v_div_scale_f32 v96, vcc, 1.0, v120, 1.0
	v_fma_f32 v97, -v121, v122, 1.0
	v_fmac_f32_e32 v122, v97, v122
	v_mul_f32_e32 v97, v96, v122
	v_fma_f32 v123, -v121, v97, v96
	v_fmac_f32_e32 v97, v123, v122
	v_fma_f32 v96, -v121, v97, v96
	v_div_fmas_f32 v96, v96, v122, v97
	v_div_fixup_f32 v96, v96, v120, 1.0
	v_pk_mul_f32 v[98:99], v[98:99], v[96:97] op_sel_hi:[1,0]
	v_pk_mul_f32 v[100:101], v[100:101], v[96:97] op_sel_hi:[1,0]
	v_pk_mul_f32 v[102:103], v[102:103], v[96:97] op_sel_hi:[1,0]
	v_pk_mul_f32 v[104:105], v[104:105], v[96:97] op_sel_hi:[1,0]
	v_pk_mul_f32 v[106:107], v[106:107], v[96:97] op_sel_hi:[1,0]
	v_pk_mul_f32 v[108:109], v[108:109], v[96:97] op_sel_hi:[1,0]
	v_pk_mul_f32 v[110:111], v[110:111], v[96:97] op_sel_hi:[1,0]
	v_pk_mul_f32 v[96:97], v[118:119], v[96:97] op_sel_hi:[1,0]
	v_pk_mul_f32 v[98:99], v[98:99], v[98:99]
	v_pk_mul_f32 v[100:101], v[100:101], v[100:101]
	v_pk_mul_f32 v[102:103], v[102:103], v[102:103]
	v_pk_mul_f32 v[104:105], v[104:105], v[104:105]
	v_pk_mul_f32 v[106:107], v[106:107], v[106:107]
	v_pk_mul_f32 v[108:109], v[108:109], v[108:109]
	v_pk_mul_f32 v[110:111], v[110:111], v[110:111]
	v_pk_mul_f32 v[118:119], v[96:97], v[96:97]
	v_cvt_pk_bf16_f32 v96, v98, v99
	v_cvt_pk_bf16_f32 v97, v102, v103
	v_cvt_pk_bf16_f32 v98, v100, v101
	v_cvt_pk_bf16_f32 v99, v104, v105
	v_cvt_pk_bf16_f32 v100, v106, v107
	v_cvt_pk_bf16_f32 v101, v110, v111
	v_cvt_pk_bf16_f32 v102, v108, v109
	v_cvt_pk_bf16_f32 v103, v118, v119
	global_store_dwordx4 v[116:117], v[96:99], off
	global_store_dwordx4 v[116:117], v[100:103], off offset:256
	s_nop 1
	v_mov_b32_e32 v96, v202
	v_mov_b32_e32 v97, v203
	v_max_f32_e32 v104, v83, v83
	v_max_f32_e32 v83, 0, v93
	v_max_f32_e32 v93, 0, v81
	v_max_f32_e32 v103, v87, v87
	v_max_f32_e32 v87, 0, v95
	v_max_f32_e32 v100, v85, v85
	v_max_f32_e32 v98, v84, v84
	v_max_f32_e32 v101, v86, v86
	v_max_f32_e32 v102, v82, v82
	v_max_f32_e32 v85, 0, v89
	v_max_f32_e32 v89, 0, v91
	v_max_f32_e32 v91, 0, v100
	v_max_f32_e32 v84, 0, v88
	v_max_f32_e32 v86, 0, v94
	v_max_f32_e32 v88, 0, v90
	v_max_f32_e32 v90, 0, v98
	v_max_f32_e32 v94, 0, v101
	v_max_f32_e32 v98, 0, v102
	v_max_f32_e32 v99, v80, v80
	v_or_b32_e32 v80, 32, v140
	v_max_f32_e32 v82, 0, v92
	v_max_f32_e32 v92, 0, v99
	v_max_f32_e32 v99, 0, v104
	v_ffbh_u32_e32 v81, v97
	v_min_u32_e32 v81, 32, v81
	v_lshlrev_b64 v[96:97], v81, v[96:97]
	v_min_u32_e32 v95, 1, v96
	v_or_b32_e32 v95, v97, v95
	v_cvt_f32_u32_e32 v96, v95
	v_sub_u32_e32 v81, 32, v81
	v_max_f32_e32 v95, 0, v103
	v_ldexp_f32 v81, v96, v81
	v_mul_f32_e32 v81, 0x35800000, v81
	v_fmamk_f32 v81, v81, 0x3a800000, v182
	v_mul_f32_e32 v96, 0x4f800000, v81
	v_cmp_gt_f32_e32 vcc, s50, v81
	s_nop 1
	v_cndmask_b32_e32 v96, v81, v96, vcc
	v_sqrt_f32_e32 v97, v96
	v_ashrrev_i32_e32 v81, 31, v80
	v_lshlrev_b64 v[80:81], 13, v[80:81]
	v_lshl_add_u64 v[80:81], s[14:15], 0, v[80:81]
	v_add_u32_e32 v100, -1, v97
	v_add_u32_e32 v101, 1, v97
	v_fma_f32 v102, -v100, v97, v96
	v_fma_f32 v103, -v101, v97, v96
	v_cmp_ge_f32_e64 s[10:11], 0, v102
	s_nop 1
	v_cndmask_b32_e64 v97, v97, v100, s[10:11]
	v_cmp_lt_f32_e64 s[10:11], 0, v103
	s_nop 1
	v_cndmask_b32_e64 v97, v97, v101, s[10:11]
	v_mul_f32_e32 v100, 0x37800000, v97
	v_cndmask_b32_e32 v97, v97, v100, vcc
	v_cmp_class_f32_e32 vcc, v96, v183
	s_nop 1
	v_cndmask_b32_e32 v100, v97, v96, vcc
	v_div_scale_f32 v101, s[10:11], v100, v100, 1.0
	v_rcp_f32_e32 v102, v101
	v_lshl_add_u64 v[96:97], v[80:81], 0, v[114:115]
	v_div_scale_f32 v80, vcc, 1.0, v100, 1.0
	v_fma_f32 v81, -v101, v102, 1.0
	v_fmac_f32_e32 v102, v81, v102
	v_mul_f32_e32 v81, v80, v102
	v_fma_f32 v103, -v101, v81, v80
	v_fmac_f32_e32 v81, v103, v102
	v_fma_f32 v80, -v101, v81, v80
	v_div_fmas_f32 v80, v80, v102, v81
	v_div_fixup_f32 v80, v80, v100, 1.0
	v_pk_mul_f32 v[82:83], v[82:83], v[80:81] op_sel_hi:[1,0]
	v_pk_mul_f32 v[84:85], v[84:85], v[80:81] op_sel_hi:[1,0]
	v_pk_mul_f32 v[86:87], v[86:87], v[80:81] op_sel_hi:[1,0]
	v_pk_mul_f32 v[88:89], v[88:89], v[80:81] op_sel_hi:[1,0]
	v_pk_mul_f32 v[90:91], v[90:91], v[80:81] op_sel_hi:[1,0]
	v_pk_mul_f32 v[92:93], v[92:93], v[80:81] op_sel_hi:[1,0]
	v_pk_mul_f32 v[94:95], v[94:95], v[80:81] op_sel_hi:[1,0]
	v_pk_mul_f32 v[80:81], v[98:99], v[80:81] op_sel_hi:[1,0]
	v_pk_mul_f32 v[82:83], v[82:83], v[82:83]
	v_pk_mul_f32 v[84:85], v[84:85], v[84:85]
	v_pk_mul_f32 v[86:87], v[86:87], v[86:87]
	v_pk_mul_f32 v[88:89], v[88:89], v[88:89]
	v_pk_mul_f32 v[90:91], v[90:91], v[90:91]
	v_pk_mul_f32 v[92:93], v[92:93], v[92:93]
	v_pk_mul_f32 v[94:95], v[94:95], v[94:95]
	v_pk_mul_f32 v[98:99], v[80:81], v[80:81]
	v_cvt_pk_bf16_f32 v80, v82, v83
	v_cvt_pk_bf16_f32 v81, v86, v87
	v_cvt_pk_bf16_f32 v82, v84, v85
	v_cvt_pk_bf16_f32 v83, v88, v89
	v_cvt_pk_bf16_f32 v84, v90, v91
	v_cvt_pk_bf16_f32 v85, v94, v95
	v_cvt_pk_bf16_f32 v86, v92, v93
	v_cvt_pk_bf16_f32 v87, v98, v99
	global_store_dwordx4 v[96:97], v[80:83], off
	global_store_dwordx4 v[96:97], v[84:87], off offset:256
	s_nop 1
	v_mov_b32_e32 v80, v204
	v_mov_b32_e32 v81, v205
	v_max_f32_e32 v88, v67, v67
	v_max_f32_e32 v67, 0, v77
	v_max_f32_e32 v77, 0, v65
	v_max_f32_e32 v87, v71, v71
	v_max_f32_e32 v71, 0, v79
	v_max_f32_e32 v84, v69, v69
	v_max_f32_e32 v82, v68, v68
	v_max_f32_e32 v85, v70, v70
	v_max_f32_e32 v86, v66, v66
	v_max_f32_e32 v69, 0, v73
	v_max_f32_e32 v73, 0, v75
	v_max_f32_e32 v75, 0, v84
	v_max_f32_e32 v68, 0, v72
	v_max_f32_e32 v70, 0, v78
	v_max_f32_e32 v72, 0, v74
	v_max_f32_e32 v74, 0, v82
	v_max_f32_e32 v78, 0, v85
	v_max_f32_e32 v82, 0, v86
	v_max_f32_e32 v83, v64, v64
	v_or_b32_e32 v64, 48, v140
	v_max_f32_e32 v66, 0, v76
	v_max_f32_e32 v76, 0, v83
	v_max_f32_e32 v83, 0, v88
	v_ffbh_u32_e32 v65, v81
	v_min_u32_e32 v65, 32, v65
	v_lshlrev_b64 v[80:81], v65, v[80:81]
	v_min_u32_e32 v79, 1, v80
	v_or_b32_e32 v79, v81, v79
	v_cvt_f32_u32_e32 v80, v79
	v_sub_u32_e32 v65, 32, v65
	v_max_f32_e32 v79, 0, v87
	v_ldexp_f32 v65, v80, v65
	v_mul_f32_e32 v65, 0x35800000, v65
	v_fmamk_f32 v65, v65, 0x3a800000, v182
	v_mul_f32_e32 v80, 0x4f800000, v65
	v_cmp_gt_f32_e32 vcc, s50, v65
	s_nop 1
	v_cndmask_b32_e32 v80, v65, v80, vcc
	v_sqrt_f32_e32 v81, v80
	v_ashrrev_i32_e32 v65, 31, v64
	v_lshlrev_b64 v[64:65], 13, v[64:65]
	v_lshl_add_u64 v[64:65], s[14:15], 0, v[64:65]
	v_add_u32_e32 v84, -1, v81
	v_add_u32_e32 v85, 1, v81
	v_fma_f32 v86, -v84, v81, v80
	v_fma_f32 v87, -v85, v81, v80
	v_cmp_ge_f32_e64 s[10:11], 0, v86
	s_nop 1
	v_cndmask_b32_e64 v81, v81, v84, s[10:11]
	v_cmp_lt_f32_e64 s[10:11], 0, v87
	s_nop 1
	v_cndmask_b32_e64 v81, v81, v85, s[10:11]
	v_mul_f32_e32 v84, 0x37800000, v81
	v_cndmask_b32_e32 v81, v81, v84, vcc
	v_cmp_class_f32_e32 vcc, v80, v183
	s_nop 1
	v_cndmask_b32_e32 v84, v81, v80, vcc
	v_div_scale_f32 v85, s[10:11], v84, v84, 1.0
	v_rcp_f32_e32 v86, v85
	v_lshl_add_u64 v[80:81], v[64:65], 0, v[114:115]
	v_div_scale_f32 v64, vcc, 1.0, v84, 1.0
	v_fma_f32 v65, -v85, v86, 1.0
	v_fmac_f32_e32 v86, v65, v86
	v_mul_f32_e32 v65, v64, v86
	v_fma_f32 v87, -v85, v65, v64
	v_fmac_f32_e32 v65, v87, v86
	v_fma_f32 v64, -v85, v65, v64
	v_div_fmas_f32 v64, v64, v86, v65
	v_div_fixup_f32 v64, v64, v84, 1.0
	v_pk_mul_f32 v[66:67], v[66:67], v[64:65] op_sel_hi:[1,0]
	v_pk_mul_f32 v[68:69], v[68:69], v[64:65] op_sel_hi:[1,0]
	v_pk_mul_f32 v[70:71], v[70:71], v[64:65] op_sel_hi:[1,0]
	v_pk_mul_f32 v[72:73], v[72:73], v[64:65] op_sel_hi:[1,0]
	v_pk_mul_f32 v[74:75], v[74:75], v[64:65] op_sel_hi:[1,0]
	v_pk_mul_f32 v[76:77], v[76:77], v[64:65] op_sel_hi:[1,0]
	v_pk_mul_f32 v[78:79], v[78:79], v[64:65] op_sel_hi:[1,0]
	v_pk_mul_f32 v[64:65], v[82:83], v[64:65] op_sel_hi:[1,0]
	v_pk_mul_f32 v[66:67], v[66:67], v[66:67]
	v_pk_mul_f32 v[68:69], v[68:69], v[68:69]
	v_pk_mul_f32 v[70:71], v[70:71], v[70:71]
	v_pk_mul_f32 v[72:73], v[72:73], v[72:73]
	v_pk_mul_f32 v[74:75], v[74:75], v[74:75]
	v_pk_mul_f32 v[76:77], v[76:77], v[76:77]
	v_pk_mul_f32 v[78:79], v[78:79], v[78:79]
	v_pk_mul_f32 v[82:83], v[64:65], v[64:65]
	v_cvt_pk_bf16_f32 v64, v66, v67
	v_cvt_pk_bf16_f32 v65, v70, v71
	v_cvt_pk_bf16_f32 v66, v68, v69
	v_cvt_pk_bf16_f32 v67, v72, v73
	v_cvt_pk_bf16_f32 v68, v74, v75
	v_cvt_pk_bf16_f32 v69, v78, v79
	v_cvt_pk_bf16_f32 v70, v76, v77
	v_cvt_pk_bf16_f32 v71, v82, v83
	global_store_dwordx4 v[80:81], v[64:67], off
	global_store_dwordx4 v[80:81], v[68:71], off offset:256
	s_nop 1
	v_mov_b32_e32 v64, v206
	v_mov_b32_e32 v65, v207
	v_max_f32_e32 v67, v48, v48
	v_max_f32_e32 v48, 0, v60
	v_max_f32_e32 v68, v53, v53
	v_max_f32_e32 v53, 0, v63
	v_max_f32_e32 v69, v49, v49
	v_max_f32_e32 v49, 0, v61
	v_max_f32_e32 v66, v52, v52
	v_max_f32_e32 v71, v50, v50
	v_max_f32_e32 v50, 0, v56
	v_max_f32_e32 v56, 0, v66
	v_max_f32_e32 v70, v54, v54
	v_max_f32_e32 v54, 0, v58
	v_max_f32_e32 v58, 0, v67
	v_max_f32_e32 v73, v51, v51
	v_max_f32_e32 v51, 0, v57
	v_max_f32_e32 v57, 0, v68
	v_max_f32_e32 v72, v55, v55
	v_max_f32_e32 v55, 0, v59
	v_max_f32_e32 v59, 0, v69
	s_mov_b64 s[10:11], 0x100000
	v_max_f32_e32 v52, 0, v62
	v_max_f32_e32 v62, 0, v71
	v_ffbh_u32_e32 v60, v65
	v_min_u32_e32 v63, 32, v60
	v_lshlrev_b64 v[60:61], v63, v[64:65]
	v_min_u32_e32 v60, 1, v60
	v_or_b32_e32 v60, v61, v60
	v_cvt_f32_u32_e32 v61, v60
	v_sub_u32_e32 v63, 32, v63
	v_max_f32_e32 v60, 0, v70
	v_lshl_add_u64 v[64:65], v[112:113], 0, s[10:11]
	v_ldexp_f32 v61, v61, v63
	v_mul_f32_e32 v61, 0x35800000, v61
	v_fmamk_f32 v61, v61, 0x3a800000, v182
	v_mul_f32_e32 v63, 0x4f800000, v61
	v_cmp_gt_f32_e32 vcc, s50, v61
	s_nop 1
	v_cndmask_b32_e32 v66, v61, v63, vcc
	v_sqrt_f32_e32 v67, v66
	v_max_f32_e32 v61, 0, v72
	v_max_f32_e32 v63, 0, v73
	v_add_u32_e32 v68, -1, v67
	v_add_u32_e32 v69, 1, v67
	v_fma_f32 v70, -v68, v67, v66
	v_fma_f32 v71, -v69, v67, v66
	v_cmp_ge_f32_e64 s[10:11], 0, v70
	s_nop 1
	v_cndmask_b32_e64 v67, v67, v68, s[10:11]
	v_cmp_lt_f32_e64 s[10:11], 0, v71
	s_nop 1
	v_cndmask_b32_e64 v67, v67, v69, s[10:11]
	v_mul_f32_e32 v68, 0x37800000, v67
	v_cndmask_b32_e32 v67, v67, v68, vcc
	v_cmp_class_f32_e32 vcc, v66, v183
	s_nop 1
	v_cndmask_b32_e32 v68, v67, v66, vcc
	v_div_scale_f32 v69, s[10:11], v68, v68, 1.0
	v_rcp_f32_e32 v70, v69
	v_add_co_u32_e32 v66, vcc, s1, v112
	s_mov_b64 s[10:11], 0x120000
	s_nop 0
	v_addc_co_u32_e32 v67, vcc, 0, v113, vcc
	v_fma_f32 v72, -v69, v70, 1.0
	v_div_scale_f32 v71, vcc, 1.0, v68, 1.0
	v_fmac_f32_e32 v70, v72, v70
	v_mul_f32_e32 v72, v71, v70
	v_fma_f32 v73, -v69, v72, v71
	v_fmac_f32_e32 v72, v73, v70
	v_fma_f32 v69, -v69, v72, v71
	v_div_fmas_f32 v69, v69, v70, v72
	v_div_fixup_f32 v68, v69, v68, 1.0
	v_pk_mul_f32 v[48:49], v[48:49], v[68:69] op_sel_hi:[1,0]
	v_pk_mul_f32 v[50:51], v[50:51], v[68:69] op_sel_hi:[1,0]
	v_pk_mul_f32 v[52:53], v[52:53], v[68:69] op_sel_hi:[1,0]
	v_pk_mul_f32 v[54:55], v[54:55], v[68:69] op_sel_hi:[1,0]
	v_pk_mul_f32 v[56:57], v[56:57], v[68:69] op_sel_hi:[1,0]
	v_pk_mul_f32 v[58:59], v[58:59], v[68:69] op_sel_hi:[1,0]
	v_pk_mul_f32 v[60:61], v[60:61], v[68:69] op_sel_hi:[1,0]
	v_pk_mul_f32 v[62:63], v[62:63], v[68:69] op_sel_hi:[1,0]
	v_pk_mul_f32 v[48:49], v[48:49], v[48:49]
	v_pk_mul_f32 v[50:51], v[50:51], v[50:51]
	v_pk_mul_f32 v[52:53], v[52:53], v[52:53]
	v_pk_mul_f32 v[54:55], v[54:55], v[54:55]
	v_pk_mul_f32 v[56:57], v[56:57], v[56:57]
	v_pk_mul_f32 v[58:59], v[58:59], v[58:59]
	v_pk_mul_f32 v[60:61], v[60:61], v[60:61]
	v_pk_mul_f32 v[62:63], v[62:63], v[62:63]
	v_cvt_pk_bf16_f32 v48, v48, v49
	v_cvt_pk_bf16_f32 v49, v52, v53
	v_cvt_pk_bf16_f32 v50, v50, v51
	v_cvt_pk_bf16_f32 v51, v54, v55
	v_cvt_pk_bf16_f32 v52, v56, v57
	v_cvt_pk_bf16_f32 v53, v60, v61
	v_cvt_pk_bf16_f32 v54, v58, v59
	v_cvt_pk_bf16_f32 v55, v62, v63
	global_store_dwordx4 v[66:67], v[48:51], off
	global_store_dwordx4 v[64:65], v[52:55], off offset:256
	s_nop 1
	v_mov_b32_e32 v48, v208
	v_mov_b32_e32 v49, v209
	v_max_f32_e32 v51, v32, v32
	v_max_f32_e32 v32, 0, v44
	v_max_f32_e32 v52, v37, v37
	v_max_f32_e32 v37, 0, v47
	v_max_f32_e32 v53, v33, v33
	v_max_f32_e32 v33, 0, v45
	v_max_f32_e32 v50, v36, v36
	v_max_f32_e32 v55, v34, v34
	v_max_f32_e32 v34, 0, v40
	v_max_f32_e32 v40, 0, v50
	v_max_f32_e32 v54, v38, v38
	v_max_f32_e32 v38, 0, v42
	v_max_f32_e32 v42, 0, v51
	v_max_f32_e32 v57, v35, v35
	v_max_f32_e32 v35, 0, v41
	v_max_f32_e32 v41, 0, v52
	v_max_f32_e32 v56, v39, v39
	v_max_f32_e32 v39, 0, v43
	v_max_f32_e32 v43, 0, v53
	v_max_f32_e32 v36, 0, v46
	v_max_f32_e32 v46, 0, v55
	s_mov_b32 s1, 0x120000
	v_ffbh_u32_e32 v44, v49
	v_min_u32_e32 v47, 32, v44
	v_lshlrev_b64 v[44:45], v47, v[48:49]
	v_min_u32_e32 v44, 1, v44
	v_or_b32_e32 v44, v45, v44
	v_cvt_f32_u32_e32 v45, v44
	v_sub_u32_e32 v47, 32, v47
	v_max_f32_e32 v44, 0, v54
	v_lshl_add_u64 v[48:49], v[112:113], 0, s[10:11]
	v_ldexp_f32 v45, v45, v47
	v_mul_f32_e32 v45, 0x35800000, v45
	v_fmamk_f32 v45, v45, 0x3a800000, v182
	v_mul_f32_e32 v47, 0x4f800000, v45
	v_cmp_gt_f32_e32 vcc, s50, v45
	s_nop 1
	v_cndmask_b32_e32 v50, v45, v47, vcc
	v_sqrt_f32_e32 v51, v50
	v_max_f32_e32 v45, 0, v56
	v_max_f32_e32 v47, 0, v57
	v_add_u32_e32 v52, -1, v51
	v_add_u32_e32 v53, 1, v51
	v_fma_f32 v54, -v52, v51, v50
	v_fma_f32 v55, -v53, v51, v50
	v_cmp_ge_f32_e64 s[10:11], 0, v54
	s_nop 1
	v_cndmask_b32_e64 v51, v51, v52, s[10:11]
	v_cmp_lt_f32_e64 s[10:11], 0, v55
	s_nop 1
	v_cndmask_b32_e64 v51, v51, v53, s[10:11]
	v_mul_f32_e32 v52, 0x37800000, v51
	v_cndmask_b32_e32 v51, v51, v52, vcc
	v_cmp_class_f32_e32 vcc, v50, v183
	s_nop 1
	v_cndmask_b32_e32 v52, v51, v50, vcc
	v_div_scale_f32 v53, s[10:11], v52, v52, 1.0
	v_rcp_f32_e32 v54, v53
	v_add_co_u32_e32 v50, vcc, s1, v112
	s_mov_b64 s[10:11], 0x140000
	s_nop 0
	v_addc_co_u32_e32 v51, vcc, 0, v113, vcc
	v_fma_f32 v56, -v53, v54, 1.0
	v_div_scale_f32 v55, vcc, 1.0, v52, 1.0
	v_fmac_f32_e32 v54, v56, v54
	v_mul_f32_e32 v56, v55, v54
	v_fma_f32 v57, -v53, v56, v55
	v_fmac_f32_e32 v56, v57, v54
	v_fma_f32 v53, -v53, v56, v55
	v_div_fmas_f32 v53, v53, v54, v56
	v_div_fixup_f32 v52, v53, v52, 1.0
	v_pk_mul_f32 v[32:33], v[32:33], v[52:53] op_sel_hi:[1,0]
	v_pk_mul_f32 v[34:35], v[34:35], v[52:53] op_sel_hi:[1,0]
	v_pk_mul_f32 v[36:37], v[36:37], v[52:53] op_sel_hi:[1,0]
	v_pk_mul_f32 v[38:39], v[38:39], v[52:53] op_sel_hi:[1,0]
	v_pk_mul_f32 v[40:41], v[40:41], v[52:53] op_sel_hi:[1,0]
	v_pk_mul_f32 v[42:43], v[42:43], v[52:53] op_sel_hi:[1,0]
	v_pk_mul_f32 v[44:45], v[44:45], v[52:53] op_sel_hi:[1,0]
	v_pk_mul_f32 v[46:47], v[46:47], v[52:53] op_sel_hi:[1,0]
	v_pk_mul_f32 v[32:33], v[32:33], v[32:33]
	v_pk_mul_f32 v[34:35], v[34:35], v[34:35]
	v_pk_mul_f32 v[36:37], v[36:37], v[36:37]
	v_pk_mul_f32 v[38:39], v[38:39], v[38:39]
	v_pk_mul_f32 v[40:41], v[40:41], v[40:41]
	v_pk_mul_f32 v[42:43], v[42:43], v[42:43]
	v_pk_mul_f32 v[44:45], v[44:45], v[44:45]
	v_pk_mul_f32 v[46:47], v[46:47], v[46:47]
	v_cvt_pk_bf16_f32 v32, v32, v33
	v_cvt_pk_bf16_f32 v33, v36, v37
	v_cvt_pk_bf16_f32 v34, v34, v35
	v_cvt_pk_bf16_f32 v35, v38, v39
	v_cvt_pk_bf16_f32 v36, v40, v41
	v_cvt_pk_bf16_f32 v37, v44, v45
	v_cvt_pk_bf16_f32 v38, v42, v43
	v_cvt_pk_bf16_f32 v39, v46, v47
	global_store_dwordx4 v[50:51], v[32:35], off
	global_store_dwordx4 v[48:49], v[36:39], off offset:256
	s_nop 1
	v_mov_b32_e32 v32, v210
	v_mov_b32_e32 v33, v211
	v_max_f32_e32 v35, v16, v16
	v_max_f32_e32 v16, 0, v28
	v_max_f32_e32 v36, v21, v21
	v_max_f32_e32 v21, 0, v31
	v_max_f32_e32 v37, v17, v17
	v_max_f32_e32 v17, 0, v29
	v_max_f32_e32 v34, v20, v20
	v_max_f32_e32 v39, v18, v18
	v_max_f32_e32 v18, 0, v24
	v_max_f32_e32 v24, 0, v34
	v_max_f32_e32 v38, v22, v22
	v_max_f32_e32 v22, 0, v26
	v_max_f32_e32 v26, 0, v35
	v_max_f32_e32 v41, v19, v19
	v_max_f32_e32 v19, 0, v25
	v_max_f32_e32 v25, 0, v36
	v_max_f32_e32 v40, v23, v23
	v_max_f32_e32 v23, 0, v27
	v_max_f32_e32 v27, 0, v37
	v_max_f32_e32 v20, 0, v30
	v_max_f32_e32 v30, 0, v39
	s_mov_b32 s1, 0x140000
	v_ffbh_u32_e32 v28, v33
	v_min_u32_e32 v31, 32, v28
	v_lshlrev_b64 v[28:29], v31, v[32:33]
	v_min_u32_e32 v28, 1, v28
	v_or_b32_e32 v28, v29, v28
	v_cvt_f32_u32_e32 v29, v28
	v_sub_u32_e32 v31, 32, v31
	v_max_f32_e32 v28, 0, v38
	v_lshl_add_u64 v[32:33], v[112:113], 0, s[10:11]
	v_ldexp_f32 v29, v29, v31
	v_mul_f32_e32 v29, 0x35800000, v29
	v_fmamk_f32 v29, v29, 0x3a800000, v182
	v_mul_f32_e32 v31, 0x4f800000, v29
	v_cmp_gt_f32_e32 vcc, s50, v29
	s_nop 1
	v_cndmask_b32_e32 v34, v29, v31, vcc
	v_sqrt_f32_e32 v35, v34
	v_max_f32_e32 v29, 0, v40
	v_max_f32_e32 v31, 0, v41
	v_add_u32_e32 v36, -1, v35
	v_add_u32_e32 v37, 1, v35
	v_fma_f32 v38, -v36, v35, v34
	v_fma_f32 v39, -v37, v35, v34
	v_cmp_ge_f32_e64 s[10:11], 0, v38
	s_nop 1
	v_cndmask_b32_e64 v35, v35, v36, s[10:11]
	v_cmp_lt_f32_e64 s[10:11], 0, v39
	s_nop 1
	v_cndmask_b32_e64 v35, v35, v37, s[10:11]
	v_mul_f32_e32 v36, 0x37800000, v35
	v_cndmask_b32_e32 v35, v35, v36, vcc
	v_cmp_class_f32_e32 vcc, v34, v183
	s_nop 1
	v_cndmask_b32_e32 v36, v35, v34, vcc
	v_div_scale_f32 v37, s[10:11], v36, v36, 1.0
	v_rcp_f32_e32 v38, v37
	v_add_co_u32_e32 v34, vcc, s1, v112
	s_mov_b64 s[10:11], 0x160000
	s_nop 0
	v_addc_co_u32_e32 v35, vcc, 0, v113, vcc
	v_fma_f32 v40, -v37, v38, 1.0
	v_div_scale_f32 v39, vcc, 1.0, v36, 1.0
	v_fmac_f32_e32 v38, v40, v38
	v_mul_f32_e32 v40, v39, v38
	v_fma_f32 v41, -v37, v40, v39
	v_fmac_f32_e32 v40, v41, v38
	v_fma_f32 v37, -v37, v40, v39
	v_div_fmas_f32 v37, v37, v38, v40
	v_div_fixup_f32 v36, v37, v36, 1.0
	v_pk_mul_f32 v[16:17], v[16:17], v[36:37] op_sel_hi:[1,0]
	v_pk_mul_f32 v[18:19], v[18:19], v[36:37] op_sel_hi:[1,0]
	v_pk_mul_f32 v[20:21], v[20:21], v[36:37] op_sel_hi:[1,0]
	v_pk_mul_f32 v[22:23], v[22:23], v[36:37] op_sel_hi:[1,0]
	v_pk_mul_f32 v[24:25], v[24:25], v[36:37] op_sel_hi:[1,0]
	v_pk_mul_f32 v[26:27], v[26:27], v[36:37] op_sel_hi:[1,0]
	v_pk_mul_f32 v[28:29], v[28:29], v[36:37] op_sel_hi:[1,0]
	v_pk_mul_f32 v[30:31], v[30:31], v[36:37] op_sel_hi:[1,0]
	v_pk_mul_f32 v[16:17], v[16:17], v[16:17]
	v_pk_mul_f32 v[18:19], v[18:19], v[18:19]
	v_pk_mul_f32 v[20:21], v[20:21], v[20:21]
	v_pk_mul_f32 v[22:23], v[22:23], v[22:23]
	v_pk_mul_f32 v[24:25], v[24:25], v[24:25]
	v_pk_mul_f32 v[26:27], v[26:27], v[26:27]
	v_pk_mul_f32 v[28:29], v[28:29], v[28:29]
	v_pk_mul_f32 v[30:31], v[30:31], v[30:31]
	v_cvt_pk_bf16_f32 v16, v16, v17
	v_cvt_pk_bf16_f32 v17, v20, v21
	v_cvt_pk_bf16_f32 v18, v18, v19
	v_cvt_pk_bf16_f32 v19, v22, v23
	v_cvt_pk_bf16_f32 v20, v24, v25
	v_cvt_pk_bf16_f32 v21, v28, v29
	v_cvt_pk_bf16_f32 v22, v26, v27
	v_cvt_pk_bf16_f32 v23, v30, v31
	global_store_dwordx4 v[34:35], v[16:19], off
	global_store_dwordx4 v[32:33], v[20:23], off offset:256
	s_nop 1
	v_mov_b32_e32 v16, v212
	v_mov_b32_e32 v17, v213
	v_max_f32_e32 v18, v4, v4
	v_max_f32_e32 v21, v1, v1
	v_max_f32_e32 v1, 0, v13
	v_max_f32_e32 v23, v2, v2
	v_max_f32_e32 v2, 0, v8
	v_max_f32_e32 v8, 0, v18
	v_max_f32_e32 v20, v5, v5
	v_max_f32_e32 v4, 0, v14
	v_max_f32_e32 v5, 0, v15
	v_max_f32_e32 v19, v0, v0
	v_max_f32_e32 v22, v6, v6
	v_max_f32_e32 v6, 0, v10
	v_max_f32_e32 v10, 0, v19
	v_max_f32_e32 v25, v3, v3
	v_max_f32_e32 v3, 0, v9
	v_max_f32_e32 v9, 0, v20
	v_max_f32_e32 v24, v7, v7
	v_max_f32_e32 v0, 0, v12
	v_max_f32_e32 v7, 0, v11
	v_max_f32_e32 v11, 0, v21
	v_max_f32_e32 v12, 0, v22
	s_mov_b32 s1, 0x160000
	v_ffbh_u32_e32 v13, v17
	v_min_u32_e32 v18, 32, v13
	v_lshlrev_b64 v[14:15], v18, v[16:17]
	v_min_u32_e32 v13, 1, v14
	v_or_b32_e32 v13, v15, v13
	v_cvt_f32_u32_e32 v15, v13
	v_sub_u32_e32 v16, 32, v18
	v_max_f32_e32 v14, 0, v23
	v_max_f32_e32 v13, 0, v24
	v_ldexp_f32 v15, v15, v16
	v_mul_f32_e32 v15, 0x35800000, v15
	v_fmamk_f32 v15, v15, 0x3a800000, v182
	v_mul_f32_e32 v16, 0x4f800000, v15
	v_cmp_gt_f32_e32 vcc, s50, v15
	s_nop 1
	v_cndmask_b32_e32 v18, v15, v16, vcc
	v_sqrt_f32_e32 v19, v18
	v_lshl_add_u64 v[16:17], v[112:113], 0, s[10:11]
	v_max_f32_e32 v15, 0, v25
	v_add_u32_e32 v20, -1, v19
	v_add_u32_e32 v21, 1, v19
	v_fma_f32 v22, -v20, v19, v18
	v_fma_f32 v23, -v21, v19, v18
	v_cmp_ge_f32_e64 s[10:11], 0, v22
	s_nop 1
	v_cndmask_b32_e64 v19, v19, v20, s[10:11]
	v_cmp_lt_f32_e64 s[10:11], 0, v23
	s_nop 1
	v_cndmask_b32_e64 v19, v19, v21, s[10:11]
	v_mul_f32_e32 v20, 0x37800000, v19
	v_cndmask_b32_e32 v19, v19, v20, vcc
	v_cmp_class_f32_e32 vcc, v18, v183
	s_nop 1
	v_cndmask_b32_e32 v20, v19, v18, vcc
	v_div_scale_f32 v21, s[10:11], v20, v20, 1.0
	v_rcp_f32_e32 v22, v21
	v_add_co_u32_e32 v18, vcc, s1, v112
	v_fma_f32 v24, -v21, v22, 1.0
	s_nop 0
	v_addc_co_u32_e32 v19, vcc, 0, v113, vcc
	v_div_scale_f32 v23, vcc, 1.0, v20, 1.0
	v_fmac_f32_e32 v22, v24, v22
	v_mul_f32_e32 v24, v23, v22
	v_fma_f32 v25, -v21, v24, v23
	v_fmac_f32_e32 v24, v25, v22
	v_fma_f32 v21, -v21, v24, v23
	v_div_fmas_f32 v21, v21, v22, v24
	v_div_fixup_f32 v20, v21, v20, 1.0
	v_pk_mul_f32 v[0:1], v[0:1], v[20:21] op_sel_hi:[1,0]
	v_pk_mul_f32 v[2:3], v[2:3], v[20:21] op_sel_hi:[1,0]
	v_pk_mul_f32 v[4:5], v[4:5], v[20:21] op_sel_hi:[1,0]
	v_pk_mul_f32 v[6:7], v[6:7], v[20:21] op_sel_hi:[1,0]
	v_pk_mul_f32 v[8:9], v[8:9], v[20:21] op_sel_hi:[1,0]
	v_pk_mul_f32 v[10:11], v[10:11], v[20:21] op_sel_hi:[1,0]
	v_pk_mul_f32 v[12:13], v[12:13], v[20:21] op_sel_hi:[1,0]
	v_pk_mul_f32 v[14:15], v[14:15], v[20:21] op_sel_hi:[1,0]
	v_pk_mul_f32 v[0:1], v[0:1], v[0:1]
	v_pk_mul_f32 v[2:3], v[2:3], v[2:3]
	v_pk_mul_f32 v[4:5], v[4:5], v[4:5]
	v_pk_mul_f32 v[6:7], v[6:7], v[6:7]
	s_andn2_b64 vcc, exec, s[8:9]
	v_pk_mul_f32 v[8:9], v[8:9], v[8:9]
	v_pk_mul_f32 v[10:11], v[10:11], v[10:11]
	v_pk_mul_f32 v[12:13], v[12:13], v[12:13]
	v_pk_mul_f32 v[14:15], v[14:15], v[14:15]
	v_cvt_pk_bf16_f32 v0, v0, v1
	v_cvt_pk_bf16_f32 v1, v4, v5
	v_cvt_pk_bf16_f32 v2, v2, v3
	v_cvt_pk_bf16_f32 v3, v6, v7
	s_mov_b64 s[8:9], -1
	v_cvt_pk_bf16_f32 v4, v8, v9
	v_cvt_pk_bf16_f32 v5, v12, v13
	v_cvt_pk_bf16_f32 v6, v10, v11
	v_cvt_pk_bf16_f32 v7, v14, v15
	global_store_dwordx4 v[18:19], v[0:3], off
	global_store_dwordx4 v[16:17], v[4:7], off offset:256
	s_cbranch_vccnz .LBB0_645
	s_andn2_b64 vcc, exec, s[12:13]
	s_cbranch_vccnz .LBB0_644
	s_barrier
	s_branch .LBB0_644
